# attn: coalesced swizzled K staging, DMA issues between QK MFMAs, tile-b exps/packs and row sums inside PV MFMA gaps
# speedup vs baseline: 1.0155x; 1.0062x over previous
.LBB0_665:
	v_mov_b32_e32 v6, v242
	s_xor_b64 s[52:53], s[38:39], -1
	v_readfirstlane_b32 s6, v6
	s_ashr_i32 s67, s6, 6
	s_and_b64 s[24:25], s[38:39], exec
	s_cselect_b32 s7, s33, s80
	s_lshl_b32 s56, s67, 5
	s_or_b32 s24, s44, s7
	s_ashr_i32 s25, s56, 31
	s_add_u32 s24, s24, s56
	s_addc_u32 s25, s45, s25
	v_bfe_u32 v251, v6, 5, 1
	s_lshl_b64 s[54:55], s[24:25], 10
	s_lshl_b64 s[24:25], s[24:25], 11
	v_lshlrev_b32_e32 v244, 3, v6
	v_lshlrev_b32_e32 v0, 1, v6
	v_and_b32_e32 v250, 31, v6
	s_add_u32 s24, s63, s24
	s_waitcnt lgkmcnt(0)
	v_and_b32_e32 v5, 24, v244
	v_and_b32_e32 v0, 32, v0
	v_lshlrev_b32_e32 v243, 4, v251
	s_addc_u32 s25, s64, s25
	v_add3_u32 v8, 0, v0, v5
	v_lshl_or_b32 v0, v250, 11, v243
	global_load_dwordx4 v[210:213], v0, s[24:25]
	global_load_dwordx4 v[214:217], v0, s[24:25] offset:32
	global_load_dwordx4 v[218:221], v0, s[24:25] offset:64
	global_load_dwordx4 v[222:225], v0, s[24:25] offset:96
	s_and_b32 s57, s6, 0x3fffffc0
	s_lshl_b32 s38, s67, 4
	v_bfe_u32 v7, v6, 2, 4
	s_ashr_i32 s6, s6, 3
	v_and_b32_e32 v249, 63, v6
	s_lshl_b32 s36, s67, 3
	v_and_or_b32 v4, s38, 48, v7
	s_and_b32 s38, s6, 0xffffffe0
	s_ashr_i32 s37, s36, 31
	s_ashr_i32 s39, s38, 31
	s_lshl_b32 s69, s67, 10
	v_lshlrev_b32_e32 v0, 11, v249
	s_cmp_lg_u32 0, -1
	v_lshl_add_u64 v[2:3], s[46:47], 0, v[0:1]
	v_lshlrev_b32_e32 v0, 11, v4
	s_cselect_b32 s6, 0, 0
	v_lshrrev_b32_e32 v238, 4, v249
	v_and_b32_e32 v239, 7, v249
	v_xor_b32_e32 v238, v238, v239
	s_and_b32 s101, s67, 1
	s_lshl_b32 s101, s101, 2
	v_xor_b32_e32 v238, s101, v238
	v_lshlrev_b32_e32 v238, 4, v238
	v_lshrrev_b32_e32 v239, 3, v249
	v_lshl_or_b32 v238, v239, 11, v238
	s_lshl_b32 s101, s67, 14
	v_add_u32_e32 v238, s101, v238
	v_mov_b32_e32 v239, 0
	v_lshl_add_u64 v[238:239], s[46:47], 0, v[238:239]
	v_lshl_add_u64 v[2:3], s[48:49], 0, v[0:1]
	s_lshl_b64 s[24:25], s[38:39], 1
	s_add_i32 s69, s69, s6
	v_lshl_add_u64 v[2:3], v[2:3], 0, s[24:25]
	v_lshlrev_b32_e32 v0, 1, v5
	s_mov_b32 s36, m0
	s_mov_b32 m0, s69
	s_nop 0
	global_load_lds_dwordx4 v[238:239], off
	s_mov_b32 m0, s36
	v_lshl_add_u64 v[2:3], v[2:3], 0, v[0:1]
	s_add_i32 s70, s69, 0x8000
	s_mov_b32 s36, m0
	s_mov_b32 m0, s70
	s_nop 0
	global_load_lds_dwordx4 v[2:3], off
	s_mov_b32 m0, s36
	v_lshl_add_u64 v[4:5], v[2:3], 0, s[84:85]
	s_add_i32 s36, s70, 0x2000
	s_mov_b32 s37, m0
	s_mov_b32 m0, s36
	s_nop 0
	global_load_lds_dwordx4 v[4:5], off
	s_mov_b32 m0, s37
	v_lshl_add_u64 v[4:5], v[238:239], 0, s[14:15]
	s_add_i32 s36, s69, 0x2000
	s_mov_b32 s37, m0
	s_mov_b32 m0, s36
	s_nop 0
	global_load_lds_dwordx4 v[4:5], off
	s_mov_b32 m0, s37
	v_lshl_add_u64 v[4:5], v[2:3], 0, s[14:15]
	s_add_i32 s36, s69, 0xc000
	s_mov_b32 s37, m0
	s_mov_b32 m0, s36
	s_nop 0
	global_load_lds_dwordx4 v[4:5], off
	s_mov_b32 m0, s37
	s_mov_b64 s[36:37], 0x20080
	v_lshlrev_b32_e32 v10, 4, v6
	v_lshl_add_u64 v[2:3], v[2:3], 0, s[36:37]
	v_lshlrev_b32_e32 v9, 8, v251
	v_and_b32_e32 v0, 0xc0, v10
	s_add_i32 s36, s69, 0xe000
	s_mov_b32 s37, m0
	s_mov_b32 m0, s36
	s_nop 0
	global_load_lds_dwordx4 v[2:3], off
	s_mov_b32 m0, s37
	v_lshlrev_b32_e32 v3, 2, v251
	s_add_i32 s6, s7, 0x100
	v_add3_u32 v230, v8, v9, v0
	v_lshlrev_b32_e32 v0, 10, v251
	v_lshlrev_b32_e32 v2, 4, v250
	v_subrev_u32_e32 v234, s7, v3
	s_lshl_b32 s7, s67, 15
	v_bfe_u32 v233, v250, 1, 3
	v_xor_b32_e32 v233, v233, v251
	v_lshlrev_b32_e32 v233, 4, v233
	v_lshl_or_b32 v233, v250, 7, v233
	v_and_b32_e32 v0, 3, v6
	s_and_b32 s7, s7, 0x18000
	v_lshl_or_b32 v2, v0, 4, s24
	v_mov_b32_e32 v3, s25
	v_lshl_or_b32 v0, v7, 11, s7
	s_lshl_b32 s36, s57, 2
	v_lshl_add_u64 v[2:3], v[2:3], 0, v[0:1]
	v_mov_b32_e32 v14, v1
	v_mov_b32_e32 v15, v1
	s_add_i32 s71, s36, 0
	v_lshl_add_u64 v[240:241], s[50:51], 0, v[2:3]
	v_mov_b32_e32 v0, v1
	v_mov_b32_e32 v2, v1
	v_mov_b32_e32 v3, v1
	v_mov_b32_e32 v4, v1
	v_mov_b32_e32 v5, v1
	v_mov_b32_e32 v6, v1
	v_mov_b32_e32 v7, v1
	v_mov_b32_e32 v8, v1
	v_mov_b32_e32 v9, v1
	v_mov_b32_e32 v10, v1
	v_mov_b32_e32 v11, v1
	v_mov_b32_e32 v12, v1
	v_mov_b32_e32 v13, v1
	s_waitcnt vmcnt(0)
	v_mov_b64_e32 v[64:65], v[14:15]
	v_mov_b64_e32 v[48:49], v[14:15]
	v_mov_b64_e32 v[32:33], v[14:15]
	s_add_i32 s71, s71, 0x18000
	s_lshr_b32 s72, s6, 7
	s_lshl_b32 s6, s6, 11
	v_mov_b32_e32 v235, 0
	v_mov_b64_e32 v[62:63], v[12:13]
	v_mov_b64_e32 v[60:61], v[10:11]
	v_mov_b64_e32 v[58:59], v[8:9]
	v_mov_b64_e32 v[56:57], v[6:7]
	v_mov_b64_e32 v[54:55], v[4:5]
	v_mov_b64_e32 v[52:53], v[2:3]
	v_mov_b64_e32 v[50:51], v[0:1]
	v_mov_b64_e32 v[46:47], v[12:13]
	v_mov_b64_e32 v[44:45], v[10:11]
	v_mov_b64_e32 v[42:43], v[8:9]
	v_mov_b64_e32 v[40:41], v[6:7]
	v_mov_b64_e32 v[38:39], v[4:5]
	v_mov_b64_e32 v[36:37], v[2:3]
	v_mov_b64_e32 v[34:35], v[0:1]
	v_mov_b64_e32 v[30:31], v[12:13]
	v_mov_b64_e32 v[28:29], v[10:11]
	v_mov_b64_e32 v[26:27], v[8:9]
	v_mov_b64_e32 v[24:25], v[6:7]
	v_mov_b64_e32 v[22:23], v[4:5]
	v_mov_b64_e32 v[20:21], v[2:3]
	v_mov_b64_e32 v[18:19], v[0:1]
	v_mov_b64_e32 v[16:17], v[14:15]
	s_mov_b32 s68, 0
	v_or_b32_e32 v232, s56, v250
	v_cmp_gt_u32_e64 s[38:39], 32, v249
	v_lshl_add_u32 v231, v250, 2, s71
	s_sub_i32 s73, 0, s72
	s_and_b32 s74, s6, 0xfc0000
	s_mov_b64 s[56:57], 0
	v_mov_b64_e32 v[14:15], v[12:13]
	v_mov_b64_e32 v[12:13], v[10:11]
	v_mov_b64_e32 v[10:11], v[8:9]
	v_mov_b64_e32 v[8:9], v[6:7]
	v_mov_b64_e32 v[6:7], v[4:5]
	v_mov_b64_e32 v[4:5], v[2:3]
	v_mov_b64_e32 v[2:3], v[0:1]
	v_mov_b32_e32 v0, 0
	s_mov_b32 s24, 0
	v_mov_b32_e32 v66, 0
	v_mov_b32_e32 v67, v235
	v_mov_b32_e32 v68, v235
	v_mov_b32_e32 v69, v235
	v_mov_b32_e32 v70, v235
	v_mov_b32_e32 v71, v235
	v_mov_b32_e32 v72, v235
	v_mov_b32_e32 v73, v235
	v_mov_b32_e32 v74, v235
	v_mov_b32_e32 v75, v235
	v_mov_b32_e32 v76, v235
	v_mov_b32_e32 v77, v235
	v_mov_b32_e32 v78, v235
	v_mov_b32_e32 v79, v235
	v_mov_b32_e32 v80, v235
	v_mov_b32_e32 v81, v235
.LBB0_666:
	s_waitcnt vmcnt(0) lgkmcnt(0)
	s_barrier
	s_and_b32 s36, s24, 1
	s_add_i32 s75, s24, 1
	v_lshl_add_u32 v226, s36, 14, v233
	v_xor_b32_e32 v228, 32, v226
	v_xor_b32_e32 v229, 64, v226
	v_xor_b32_e32 v236, 0x60, v226
	ds_read_b128 v[82:85], v226
	ds_read_b128 v[86:89], v226 offset:4096
	ds_read_b128 v[90:93], v228
	ds_read_b128 v[94:97], v228 offset:4096
	ds_read_b128 v[98:101], v229
	ds_read_b128 v[102:105], v229 offset:4096
	ds_read_b128 v[106:109], v236
	ds_read_b128 v[110:113], v236 offset:4096
	ds_read_b128 v[114:117], v226 offset:8192
	ds_read_b128 v[118:121], v226 offset:12288
	ds_read_b128 v[122:125], v228 offset:8192
	ds_read_b128 v[126:129], v228 offset:12288
	ds_read_b128 v[130:133], v229 offset:8192
	ds_read_b128 v[134:137], v229 offset:12288
	ds_read_b128 v[138:141], v236 offset:8192
	s_cmp_ge_u32 s75, s72
	s_cbranch_scc1 .Lattn_qk_nodma
	s_mov_b32 s37, m0
	s_xor_b32 s6, s36, 1
	s_lshl_b32 s7, s6, 14
	s_add_i32 s7, s7, s69
	s_lshl_b32 s6, s6, 15
	s_add_i32 s6, s6, s70
	s_waitcnt lgkmcnt(14)
	v_mfma_f32_32x32x16_bf16 v[146:161], v[82:85], v[210:213], v[66:81]
	ds_read_b128 v[142:145], v236 offset:12288
	s_waitcnt lgkmcnt(14)
	v_mfma_f32_32x32x16_bf16 v[162:177], v[86:89], v[210:213], v[66:81]
	v_lshl_add_u64 v[82:83], v[238:239], 0, s[56:57]
	v_lshl_add_u64 v[84:85], v[240:241], 0, s[56:57]
	s_mov_b64 s[58:59], 0x40000
	v_lshl_add_u64 v[86:87], v[82:83], 0, s[58:59]
	s_mov_b32 m0, s7
	s_nop 0
	global_load_lds_dwordx4 v[86:87], off
	s_waitcnt lgkmcnt(13)
	v_mfma_f32_32x32x16_bf16 v[146:161], v[90:93], v[214:217], v[146:161]
	s_waitcnt lgkmcnt(12)
	v_mfma_f32_32x32x16_bf16 v[162:177], v[94:97], v[214:217], v[162:177]
	s_mov_b64 s[58:59], 0x20040000
	v_lshl_add_u64 v[86:87], v[84:85], 0, s[58:59]
	s_mov_b32 m0, s6
	s_nop 0
	global_load_lds_dwordx4 v[86:87], off
	s_waitcnt lgkmcnt(11)
	v_mfma_f32_32x32x16_bf16 v[146:161], v[98:101], v[218:221], v[146:161]
	s_waitcnt lgkmcnt(10)
	v_mfma_f32_32x32x16_bf16 v[162:177], v[102:105], v[218:221], v[162:177]
	s_mov_b64 s[58:59], 0x20040080
	v_lshl_add_u64 v[86:87], v[84:85], 0, s[58:59]
	s_add_i32 m0, s6, 0x2000
	s_nop 0
	global_load_lds_dwordx4 v[86:87], off
	s_waitcnt lgkmcnt(9)
	v_mfma_f32_32x32x16_bf16 v[146:161], v[106:109], v[222:225], v[146:161]
	s_waitcnt lgkmcnt(8)
	v_mfma_f32_32x32x16_bf16 v[162:177], v[110:113], v[222:225], v[162:177]
	s_mov_b64 s[58:59], 0x60000
	v_lshl_add_u64 v[86:87], v[82:83], 0, s[58:59]
	s_add_i32 m0, s7, 0x2000
	s_nop 0
	global_load_lds_dwordx4 v[86:87], off
	s_waitcnt lgkmcnt(7)
	v_mfma_f32_32x32x16_bf16 v[178:193], v[114:117], v[210:213], v[66:81]
	s_waitcnt lgkmcnt(6)
	v_mfma_f32_32x32x16_bf16 v[194:209], v[118:121], v[210:213], v[66:81]
	s_mov_b64 s[58:59], 0x20060000
	v_lshl_add_u64 v[86:87], v[84:85], 0, s[58:59]
	s_add_i32 m0, s6, 0x4000
	s_nop 0
	global_load_lds_dwordx4 v[86:87], off
	s_waitcnt lgkmcnt(5)
	v_mfma_f32_32x32x16_bf16 v[178:193], v[122:125], v[214:217], v[178:193]
	s_waitcnt lgkmcnt(4)
	v_mfma_f32_32x32x16_bf16 v[194:209], v[126:129], v[214:217], v[194:209]
	s_mov_b64 s[58:59], 0x20060080
	v_lshl_add_u64 v[86:87], v[84:85], 0, s[58:59]
	s_add_i32 m0, s6, 0x6000
	s_nop 0
	global_load_lds_dwordx4 v[86:87], off
	s_waitcnt lgkmcnt(3)
	v_mfma_f32_32x32x16_bf16 v[178:193], v[130:133], v[218:221], v[178:193]
	s_waitcnt lgkmcnt(2)
	v_mfma_f32_32x32x16_bf16 v[194:209], v[134:137], v[218:221], v[194:209]
	s_waitcnt lgkmcnt(1)
	v_mfma_f32_32x32x16_bf16 v[178:193], v[138:141], v[222:225], v[178:193]
	s_waitcnt lgkmcnt(0)
	v_mfma_f32_32x32x16_bf16 v[194:209], v[142:145], v[222:225], v[194:209]
	s_mov_b32 m0, s37
	s_branch .Lattn_qk_done
.Lattn_qk_nodma:
	s_waitcnt lgkmcnt(14)
	v_mfma_f32_32x32x16_bf16 v[146:161], v[82:85], v[210:213], v[66:81]
	ds_read_b128 v[142:145], v236 offset:12288
	s_waitcnt lgkmcnt(14)
	v_mfma_f32_32x32x16_bf16 v[162:177], v[86:89], v[210:213], v[66:81]
	s_waitcnt lgkmcnt(13)
	v_mfma_f32_32x32x16_bf16 v[146:161], v[90:93], v[214:217], v[146:161]
	s_waitcnt lgkmcnt(12)
	v_mfma_f32_32x32x16_bf16 v[162:177], v[94:97], v[214:217], v[162:177]
	s_waitcnt lgkmcnt(11)
	v_mfma_f32_32x32x16_bf16 v[146:161], v[98:101], v[218:221], v[146:161]
	s_waitcnt lgkmcnt(10)
	v_mfma_f32_32x32x16_bf16 v[162:177], v[102:105], v[218:221], v[162:177]
	s_waitcnt lgkmcnt(9)
	v_mfma_f32_32x32x16_bf16 v[146:161], v[106:109], v[222:225], v[146:161]
	s_waitcnt lgkmcnt(8)
	v_mfma_f32_32x32x16_bf16 v[162:177], v[110:113], v[222:225], v[162:177]
	s_waitcnt lgkmcnt(7)
	v_mfma_f32_32x32x16_bf16 v[178:193], v[114:117], v[210:213], v[66:81]
	s_waitcnt lgkmcnt(6)
	v_mfma_f32_32x32x16_bf16 v[194:209], v[118:121], v[210:213], v[66:81]
	s_waitcnt lgkmcnt(5)
	v_mfma_f32_32x32x16_bf16 v[178:193], v[122:125], v[214:217], v[178:193]
	s_waitcnt lgkmcnt(4)
	v_mfma_f32_32x32x16_bf16 v[194:209], v[126:129], v[214:217], v[194:209]
	s_waitcnt lgkmcnt(3)
	v_mfma_f32_32x32x16_bf16 v[178:193], v[130:133], v[218:221], v[178:193]
	s_waitcnt lgkmcnt(2)
	v_mfma_f32_32x32x16_bf16 v[194:209], v[134:137], v[218:221], v[194:209]
	s_waitcnt lgkmcnt(1)
	v_mfma_f32_32x32x16_bf16 v[178:193], v[138:141], v[222:225], v[178:193]
	s_waitcnt lgkmcnt(0)
	v_mfma_f32_32x32x16_bf16 v[194:209], v[142:145], v[222:225], v[194:209]
.Lattn_qk_done:
	s_add_i32 s6, s73, s24
	s_cmp_lt_i32 s6, -2
	s_cbranch_scc1 .LBB0_670
	v_add_u32_e32 v82, s68, v234
	v_add_u32_e32 v83, 32, v82
	v_cmp_le_i32_e32 vcc, v83, v232
	v_add_u32_e32 v83, 33, v82
	v_add_u32_e32 v84, 0x60, v82
	v_cndmask_b32_e32 v162, v247, v162, vcc
	v_cmp_lt_i32_e32 vcc, v82, v232
	s_nop 1
	v_cndmask_b32_e32 v147, v247, v147, vcc
	v_cmp_le_i32_e32 vcc, v82, v232
	s_nop 1
	v_cndmask_b32_e32 v146, v247, v146, vcc
	v_cmp_le_i32_e32 vcc, v83, v232
	v_add_u32_e32 v83, 2, v82
	s_nop 0
	v_cndmask_b32_e32 v163, v247, v163, vcc
	v_cmp_le_i32_e32 vcc, v83, v232
	v_add_u32_e32 v83, 34, v82
	s_nop 0
	v_cndmask_b32_e32 v148, v247, v148, vcc
	v_cmp_le_i32_e32 vcc, v83, v232
	v_add_u32_e32 v83, 3, v82
	s_nop 0
	v_cndmask_b32_e32 v164, v247, v164, vcc
	v_cmp_le_i32_e32 vcc, v83, v232
	v_add_u32_e32 v83, 35, v82
	s_nop 0
	v_cndmask_b32_e32 v149, v247, v149, vcc
	v_cmp_le_i32_e32 vcc, v83, v232
	v_add_u32_e32 v83, 8, v82
	s_nop 0
	v_cndmask_b32_e32 v165, v247, v165, vcc
	v_cmp_le_i32_e32 vcc, v83, v232
	v_add_u32_e32 v83, 40, v82
	s_nop 0
	v_cndmask_b32_e32 v150, v247, v150, vcc
	v_cmp_le_i32_e32 vcc, v83, v232
	v_add_u32_e32 v83, 9, v82
	s_nop 0
	v_cndmask_b32_e32 v166, v247, v166, vcc
	v_cmp_le_i32_e32 vcc, v83, v232
	v_add_u32_e32 v83, 41, v82
	s_nop 0
	v_cndmask_b32_e32 v151, v247, v151, vcc
	v_cmp_le_i32_e32 vcc, v83, v232
	v_add_u32_e32 v83, 10, v82
	s_nop 0
	v_cndmask_b32_e32 v167, v247, v167, vcc
	v_cmp_le_i32_e32 vcc, v83, v232
	v_add_u32_e32 v83, 42, v82
	s_nop 0
	v_cndmask_b32_e32 v152, v247, v152, vcc
	v_cmp_le_i32_e32 vcc, v83, v232
	v_add_u32_e32 v83, 11, v82
	s_nop 0
	v_cndmask_b32_e32 v168, v247, v168, vcc
	v_cmp_le_i32_e32 vcc, v83, v232
	v_add_u32_e32 v83, 43, v82
	s_nop 0
	v_cndmask_b32_e32 v153, v247, v153, vcc
	v_cmp_le_i32_e32 vcc, v83, v232
	v_add_u32_e32 v83, 16, v82
	s_nop 0
	v_cndmask_b32_e32 v169, v247, v169, vcc
	v_cmp_le_i32_e32 vcc, v83, v232
	v_add_u32_e32 v83, 48, v82
	s_nop 0
	v_cndmask_b32_e32 v154, v247, v154, vcc
	v_cmp_le_i32_e32 vcc, v83, v232
	v_add_u32_e32 v83, 17, v82
	s_nop 0
	v_cndmask_b32_e32 v170, v247, v170, vcc
	v_cmp_le_i32_e32 vcc, v83, v232
	v_add_u32_e32 v83, 49, v82
	s_nop 0
	v_cndmask_b32_e32 v155, v247, v155, vcc
	v_cmp_le_i32_e32 vcc, v83, v232
	v_add_u32_e32 v83, 18, v82
	s_nop 0
	v_cndmask_b32_e32 v171, v247, v171, vcc
	v_cmp_le_i32_e32 vcc, v83, v232
	v_add_u32_e32 v83, 50, v82
	s_nop 0
	v_cndmask_b32_e32 v156, v247, v156, vcc
	v_cmp_le_i32_e32 vcc, v83, v232
	v_add_u32_e32 v83, 19, v82
	s_nop 0
	v_cndmask_b32_e32 v172, v247, v172, vcc
	v_cmp_le_i32_e32 vcc, v83, v232
	v_add_u32_e32 v83, 51, v82
	s_nop 0
	v_cndmask_b32_e32 v157, v247, v157, vcc
	v_cmp_le_i32_e32 vcc, v83, v232
	v_add_u32_e32 v83, 24, v82
	s_nop 0
	v_cndmask_b32_e32 v173, v247, v173, vcc
	v_cmp_le_i32_e32 vcc, v83, v232
	v_add_u32_e32 v83, 56, v82
	s_nop 0
	v_cndmask_b32_e32 v158, v247, v158, vcc
	v_cmp_le_i32_e32 vcc, v83, v232
	v_add_u32_e32 v83, 25, v82
	s_nop 0
	v_cndmask_b32_e32 v174, v247, v174, vcc
	v_cmp_le_i32_e32 vcc, v83, v232
	v_add_u32_e32 v83, 57, v82
	s_nop 0
	v_cndmask_b32_e32 v159, v247, v159, vcc
	v_cmp_le_i32_e32 vcc, v83, v232
	v_add_u32_e32 v83, 26, v82
	s_nop 0
	v_cndmask_b32_e32 v175, v247, v175, vcc
	v_cmp_le_i32_e32 vcc, v83, v232
	v_add_u32_e32 v83, 58, v82
	s_nop 0
	v_cndmask_b32_e32 v160, v247, v160, vcc
	v_cmp_le_i32_e32 vcc, v83, v232
	v_add_u32_e32 v83, 27, v82
	s_nop 0
	v_cndmask_b32_e32 v176, v247, v176, vcc
	v_cmp_le_i32_e32 vcc, v83, v232
	v_add_u32_e32 v83, 59, v82
	s_nop 0
	v_cndmask_b32_e32 v161, v247, v161, vcc
	v_cmp_le_i32_e32 vcc, v83, v232
	v_add_u32_e32 v83, 64, v82
	s_nop 0
	v_cndmask_b32_e32 v177, v247, v177, vcc
	v_cmp_le_i32_e32 vcc, v84, v232
	s_nop 1
	v_cndmask_b32_e32 v194, v247, v194, vcc
	v_cmp_lt_i32_e32 vcc, v83, v232
	s_nop 1
	v_cndmask_b32_e32 v179, v247, v179, vcc
	v_cmp_le_i32_e32 vcc, v83, v232
	v_add_u32_e32 v83, 0x61, v82
	s_nop 0
	v_cndmask_b32_e32 v178, v247, v178, vcc
	v_cmp_le_i32_e32 vcc, v83, v232
	v_add_u32_e32 v83, 0x42, v82
	s_nop 0
	v_cndmask_b32_e32 v195, v247, v195, vcc
	v_cmp_le_i32_e32 vcc, v83, v232
	v_add_u32_e32 v83, 0x62, v82
	s_nop 0
	v_cndmask_b32_e32 v180, v247, v180, vcc
	v_cmp_le_i32_e32 vcc, v83, v232
	v_add_u32_e32 v83, 0x43, v82
	s_nop 0
	v_cndmask_b32_e32 v196, v247, v196, vcc
	v_cmp_le_i32_e32 vcc, v83, v232
	v_add_u32_e32 v83, 0x63, v82
	s_nop 0
	v_cndmask_b32_e32 v181, v247, v181, vcc
	v_cmp_le_i32_e32 vcc, v83, v232
	v_add_u32_e32 v83, 0x48, v82
	s_nop 0
	v_cndmask_b32_e32 v197, v247, v197, vcc
	v_cmp_le_i32_e32 vcc, v83, v232
	v_add_u32_e32 v83, 0x68, v82
	s_nop 0
	v_cndmask_b32_e32 v182, v247, v182, vcc
	v_cmp_le_i32_e32 vcc, v83, v232
	v_add_u32_e32 v83, 0x49, v82
	s_nop 0
	v_cndmask_b32_e32 v198, v247, v198, vcc
	v_cmp_le_i32_e32 vcc, v83, v232
	v_add_u32_e32 v83, 0x69, v82
	s_nop 0
	v_cndmask_b32_e32 v183, v247, v183, vcc
	v_cmp_le_i32_e32 vcc, v83, v232
	v_add_u32_e32 v83, 0x4a, v82
	s_nop 0
	v_cndmask_b32_e32 v199, v247, v199, vcc
	v_cmp_le_i32_e32 vcc, v83, v232
	v_add_u32_e32 v83, 0x6a, v82
	s_nop 0
	v_cndmask_b32_e32 v184, v247, v184, vcc
	v_cmp_le_i32_e32 vcc, v83, v232
	v_add_u32_e32 v83, 0x4b, v82
	s_nop 0
	v_cndmask_b32_e32 v200, v247, v200, vcc
	v_cmp_le_i32_e32 vcc, v83, v232
	v_add_u32_e32 v83, 0x6b, v82
	s_nop 0
	v_cndmask_b32_e32 v185, v247, v185, vcc
	v_cmp_le_i32_e32 vcc, v83, v232
	v_add_u32_e32 v83, 0x50, v82
	s_nop 0
	v_cndmask_b32_e32 v201, v247, v201, vcc
	v_cmp_le_i32_e32 vcc, v83, v232
	v_add_u32_e32 v83, 0x70, v82
	s_nop 0
	v_cndmask_b32_e32 v186, v247, v186, vcc
	v_cmp_le_i32_e32 vcc, v83, v232
	v_add_u32_e32 v83, 0x51, v82
	s_nop 0
	v_cndmask_b32_e32 v202, v247, v202, vcc
	v_cmp_le_i32_e32 vcc, v83, v232
	v_add_u32_e32 v83, 0x71, v82
	s_nop 0
	v_cndmask_b32_e32 v187, v247, v187, vcc
	v_cmp_le_i32_e32 vcc, v83, v232
	v_add_u32_e32 v83, 0x52, v82
	s_nop 0
	v_cndmask_b32_e32 v203, v247, v203, vcc
	v_cmp_le_i32_e32 vcc, v83, v232
	v_add_u32_e32 v83, 0x72, v82
	s_nop 0
	v_cndmask_b32_e32 v188, v247, v188, vcc
	v_cmp_le_i32_e32 vcc, v83, v232
	v_add_u32_e32 v83, 0x53, v82
	s_nop 0
	v_cndmask_b32_e32 v204, v247, v204, vcc
	v_cmp_le_i32_e32 vcc, v83, v232
	v_add_u32_e32 v83, 0x73, v82
	s_nop 0
	v_cndmask_b32_e32 v189, v247, v189, vcc
	v_cmp_le_i32_e32 vcc, v83, v232
	v_add_u32_e32 v83, 0x58, v82
	s_nop 0
	v_cndmask_b32_e32 v205, v247, v205, vcc
	v_cmp_le_i32_e32 vcc, v83, v232
	v_add_u32_e32 v83, 0x78, v82
	s_nop 0
	v_cndmask_b32_e32 v190, v247, v190, vcc
	v_cmp_le_i32_e32 vcc, v83, v232
	v_add_u32_e32 v83, 0x59, v82
	s_nop 0
	v_cndmask_b32_e32 v206, v247, v206, vcc
	v_cmp_le_i32_e32 vcc, v83, v232
	v_add_u32_e32 v83, 0x79, v82
	s_nop 0
	v_cndmask_b32_e32 v191, v247, v191, vcc
	v_cmp_le_i32_e32 vcc, v83, v232
	v_add_u32_e32 v83, 0x5a, v82
	s_nop 0
	v_cndmask_b32_e32 v207, v247, v207, vcc
	v_cmp_le_i32_e32 vcc, v83, v232
	v_add_u32_e32 v83, 0x7a, v82
	s_nop 0
	v_cndmask_b32_e32 v192, v247, v192, vcc
	v_cmp_le_i32_e32 vcc, v83, v232
	v_add_u32_e32 v83, 0x5b, v82
	v_add_u32_e32 v82, 0x7b, v82
	v_cndmask_b32_e32 v208, v247, v208, vcc
	v_cmp_le_i32_e32 vcc, v83, v232
	s_nop 1
	v_cndmask_b32_e32 v193, v247, v193, vcc
	v_cmp_le_i32_e32 vcc, v82, v232
	s_nop 1
	v_cndmask_b32_e32 v209, v247, v209, vcc

.LBB0_679:
	v_lshl_add_u32 v227, s36, 15, v230
	ds_read_b64_tr_b16 v[114:115], v227 offset:32768
	ds_read_b64_tr_b16 v[116:117], v227 offset:33280
	ds_read_b64_tr_b16 v[118:119], v227 offset:33792
	ds_read_b64_tr_b16 v[120:121], v227 offset:34304
	ds_read_b64_tr_b16 v[122:123], v227 offset:34816
	ds_read_b64_tr_b16 v[124:125], v227 offset:35328
	ds_read_b64_tr_b16 v[126:127], v227 offset:35840
	ds_read_b64_tr_b16 v[128:129], v227 offset:36352
	ds_read_b64_tr_b16 v[130:131], v227 offset:36864
	ds_read_b64_tr_b16 v[132:133], v227 offset:37376
	ds_read_b64_tr_b16 v[134:135], v227 offset:37888
	ds_read_b64_tr_b16 v[136:137], v227 offset:38400
	v_exp_f32_e32 v146, v146
	v_exp_f32_e32 v147, v147
	v_exp_f32_e32 v162, v162
	v_exp_f32_e32 v163, v163
	v_exp_f32_e32 v148, v148
	v_exp_f32_e32 v149, v149
	v_exp_f32_e32 v164, v164
	v_exp_f32_e32 v165, v165
	v_cvt_pk_bf16_f32 v82, v146, v147
	v_cvt_pk_bf16_f32 v90, v162, v163
	v_exp_f32_e32 v150, v150
	v_exp_f32_e32 v151, v151
	v_exp_f32_e32 v166, v166
	v_exp_f32_e32 v167, v167
	v_cvt_pk_bf16_f32 v83, v148, v149
	v_cvt_pk_bf16_f32 v91, v164, v165
	v_exp_f32_e32 v152, v152
	v_exp_f32_e32 v153, v153
	v_exp_f32_e32 v168, v168
	v_exp_f32_e32 v169, v169
	v_cvt_pk_bf16_f32 v84, v150, v151
	v_cvt_pk_bf16_f32 v92, v166, v167
	v_exp_f32_e32 v154, v154
	v_exp_f32_e32 v155, v155
	v_exp_f32_e32 v170, v170
	v_exp_f32_e32 v171, v171
	v_cvt_pk_bf16_f32 v85, v152, v153
	v_cvt_pk_bf16_f32 v93, v168, v169
	v_exp_f32_e32 v156, v156
	v_exp_f32_e32 v157, v157
	v_exp_f32_e32 v172, v172
	v_exp_f32_e32 v173, v173
	v_cvt_pk_bf16_f32 v86, v154, v155
	v_cvt_pk_bf16_f32 v94, v170, v171
	v_exp_f32_e32 v158, v158
	v_exp_f32_e32 v159, v159
	v_exp_f32_e32 v174, v174
	v_exp_f32_e32 v175, v175
	v_cvt_pk_bf16_f32 v87, v156, v157
	v_cvt_pk_bf16_f32 v95, v172, v173
	v_exp_f32_e32 v160, v160
	v_exp_f32_e32 v161, v161
	v_exp_f32_e32 v176, v176
	v_exp_f32_e32 v177, v177
	v_cvt_pk_bf16_f32 v88, v158, v159
	v_cvt_pk_bf16_f32 v96, v174, v175
	s_nop 0
	v_cvt_pk_bf16_f32 v89, v160, v161
	v_cvt_pk_bf16_f32 v97, v176, v177
	s_waitcnt lgkmcnt(10)
	v_mfma_f32_32x32x16_bf16 v[50:65], v[82:85], v[114:117], v[50:65]
	ds_read_b64_tr_b16 v[138:139], v227 offset:38912
	ds_read_b64_tr_b16 v[140:141], v227 offset:39424
	v_exp_f32_e32 v178, v178
	v_exp_f32_e32 v179, v179
	s_waitcnt lgkmcnt(10)
	v_mfma_f32_32x32x16_bf16 v[50:65], v[86:89], v[118:121], v[50:65]
	ds_read_b64_tr_b16 v[142:143], v227 offset:39936
	ds_read_b64_tr_b16 v[144:145], v227 offset:40448
	v_exp_f32_e32 v180, v180
	v_exp_f32_e32 v181, v181
	v_cvt_pk_bf16_f32 v98, v178, v179
	s_waitcnt lgkmcnt(10)
	v_mfma_f32_32x32x16_bf16 v[50:65], v[90:93], v[122:125], v[50:65]
	ds_read_b64_tr_b16 v[114:115], v227 offset:40960
	ds_read_b64_tr_b16 v[116:117], v227 offset:41472
	v_exp_f32_e32 v182, v182
	v_exp_f32_e32 v183, v183
	v_cvt_pk_bf16_f32 v99, v180, v181
	s_waitcnt lgkmcnt(10)
	v_mfma_f32_32x32x16_bf16 v[50:65], v[94:97], v[126:129], v[50:65]
	ds_read_b64_tr_b16 v[118:119], v227 offset:41984
	ds_read_b64_tr_b16 v[120:121], v227 offset:42496
	v_exp_f32_e32 v184, v184
	v_exp_f32_e32 v185, v185
	v_cvt_pk_bf16_f32 v100, v182, v183
	s_waitcnt lgkmcnt(10)
	v_mfma_f32_32x32x16_bf16 v[34:49], v[82:85], v[130:133], v[34:49]
	ds_read_b64_tr_b16 v[122:123], v227 offset:43008
	ds_read_b64_tr_b16 v[124:125], v227 offset:43520
	v_exp_f32_e32 v186, v186
	v_exp_f32_e32 v187, v187
	v_cvt_pk_bf16_f32 v101, v184, v185
	s_waitcnt lgkmcnt(10)
	v_mfma_f32_32x32x16_bf16 v[34:49], v[86:89], v[134:137], v[34:49]
	ds_read_b64_tr_b16 v[126:127], v227 offset:44032
	ds_read_b64_tr_b16 v[128:129], v227 offset:44544
	v_exp_f32_e32 v188, v188
	v_exp_f32_e32 v189, v189
	v_cvt_pk_bf16_f32 v102, v186, v187
	s_waitcnt lgkmcnt(10)
	v_mfma_f32_32x32x16_bf16 v[34:49], v[90:93], v[138:141], v[34:49]
	ds_read_b64_tr_b16 v[130:131], v227 offset:45056
	ds_read_b64_tr_b16 v[132:133], v227 offset:45568
	v_exp_f32_e32 v190, v190
	v_exp_f32_e32 v191, v191
	v_cvt_pk_bf16_f32 v103, v188, v189
	s_waitcnt lgkmcnt(10)
	v_mfma_f32_32x32x16_bf16 v[34:49], v[94:97], v[142:145], v[34:49]
	ds_read_b64_tr_b16 v[134:135], v227 offset:46080
	ds_read_b64_tr_b16 v[136:137], v227 offset:46592
	v_exp_f32_e32 v192, v192
	v_exp_f32_e32 v193, v193
	v_cvt_pk_bf16_f32 v104, v190, v191
	s_waitcnt lgkmcnt(10)
	v_mfma_f32_32x32x16_bf16 v[18:33], v[82:85], v[114:117], v[18:33]
	ds_read_b64_tr_b16 v[138:139], v227 offset:47104
	ds_read_b64_tr_b16 v[140:141], v227 offset:47616
	v_exp_f32_e32 v194, v194
	v_exp_f32_e32 v195, v195
	v_cvt_pk_bf16_f32 v105, v192, v193
	s_waitcnt lgkmcnt(10)
	v_mfma_f32_32x32x16_bf16 v[18:33], v[86:89], v[118:121], v[18:33]
	ds_read_b64_tr_b16 v[142:143], v227 offset:48128
	ds_read_b64_tr_b16 v[144:145], v227 offset:48640
	v_exp_f32_e32 v196, v196
	v_exp_f32_e32 v197, v197
	v_cvt_pk_bf16_f32 v106, v194, v195
	s_waitcnt lgkmcnt(10)
	v_mfma_f32_32x32x16_bf16 v[18:33], v[90:93], v[122:125], v[18:33]
	ds_read_b64_tr_b16 v[114:115], v227 offset:49152
	ds_read_b64_tr_b16 v[116:117], v227 offset:49664
	v_exp_f32_e32 v198, v198
	v_exp_f32_e32 v199, v199
	v_cvt_pk_bf16_f32 v107, v196, v197
	s_waitcnt lgkmcnt(10)
	v_mfma_f32_32x32x16_bf16 v[18:33], v[94:97], v[126:129], v[18:33]
	ds_read_b64_tr_b16 v[118:119], v227 offset:50176
	ds_read_b64_tr_b16 v[120:121], v227 offset:50688
	v_exp_f32_e32 v200, v200
	v_exp_f32_e32 v201, v201
	v_cvt_pk_bf16_f32 v108, v198, v199
	s_waitcnt lgkmcnt(10)
	v_mfma_f32_32x32x16_bf16 v[2:17], v[82:85], v[130:133], v[2:17]
	ds_read_b64_tr_b16 v[122:123], v227 offset:51200
	ds_read_b64_tr_b16 v[124:125], v227 offset:51712
	v_exp_f32_e32 v202, v202
	v_exp_f32_e32 v203, v203
	v_cvt_pk_bf16_f32 v109, v200, v201
	s_waitcnt lgkmcnt(10)
	v_mfma_f32_32x32x16_bf16 v[2:17], v[86:89], v[134:137], v[2:17]
	ds_read_b64_tr_b16 v[126:127], v227 offset:52224
	ds_read_b64_tr_b16 v[128:129], v227 offset:52736
	v_exp_f32_e32 v204, v204
	v_exp_f32_e32 v205, v205
	v_cvt_pk_bf16_f32 v110, v202, v203
	s_waitcnt lgkmcnt(10)
	v_mfma_f32_32x32x16_bf16 v[2:17], v[90:93], v[138:141], v[2:17]
	ds_read_b64_tr_b16 v[130:131], v227 offset:53248
	ds_read_b64_tr_b16 v[132:133], v227 offset:53760
	v_exp_f32_e32 v206, v206
	v_exp_f32_e32 v207, v207
	v_cvt_pk_bf16_f32 v111, v204, v205
	s_waitcnt lgkmcnt(10)
	v_mfma_f32_32x32x16_bf16 v[2:17], v[94:97], v[142:145], v[2:17]
	ds_read_b64_tr_b16 v[134:135], v227 offset:54272
	ds_read_b64_tr_b16 v[136:137], v227 offset:54784
	v_exp_f32_e32 v208, v208
	v_exp_f32_e32 v209, v209
	v_cvt_pk_bf16_f32 v112, v206, v207
	s_waitcnt lgkmcnt(10)
	v_mfma_f32_32x32x16_bf16 v[50:65], v[98:101], v[114:117], v[50:65]
	ds_read_b64_tr_b16 v[138:139], v227 offset:55296
	ds_read_b64_tr_b16 v[140:141], v227 offset:55808
	v_cvt_pk_bf16_f32 v113, v208, v209
	v_add_f32_e32 v226, v162, v146
	v_add_f32_e32 v0, v194, v178
	s_waitcnt lgkmcnt(10)
	v_mfma_f32_32x32x16_bf16 v[50:65], v[102:105], v[118:121], v[50:65]
	ds_read_b64_tr_b16 v[142:143], v227 offset:56320
	ds_read_b64_tr_b16 v[144:145], v227 offset:56832
	v_add_f32_e32 v228, v163, v147
	v_add_f32_e32 v229, v195, v179
	v_add_f32_e32 v226, v228, v226
	v_add_f32_e32 v0, v229, v0
	s_waitcnt lgkmcnt(10)
	v_mfma_f32_32x32x16_bf16 v[50:65], v[106:109], v[122:125], v[50:65]
	ds_read_b64_tr_b16 v[114:115], v227 offset:57344
	ds_read_b64_tr_b16 v[116:117], v227 offset:57856
	v_add_f32_e32 v228, v164, v148
	v_add_f32_e32 v229, v196, v180
	v_add_f32_e32 v226, v228, v226
	v_add_f32_e32 v0, v229, v0
	s_waitcnt lgkmcnt(10)
	v_mfma_f32_32x32x16_bf16 v[50:65], v[110:113], v[126:129], v[50:65]
	ds_read_b64_tr_b16 v[118:119], v227 offset:58368
	ds_read_b64_tr_b16 v[120:121], v227 offset:58880
	v_add_f32_e32 v228, v165, v149
	v_add_f32_e32 v229, v197, v181
	v_add_f32_e32 v226, v228, v226
	v_add_f32_e32 v0, v229, v0
	s_waitcnt lgkmcnt(10)
	v_mfma_f32_32x32x16_bf16 v[34:49], v[98:101], v[130:133], v[34:49]
	ds_read_b64_tr_b16 v[122:123], v227 offset:59392
	ds_read_b64_tr_b16 v[124:125], v227 offset:59904
	v_add_f32_e32 v228, v166, v150
	v_add_f32_e32 v229, v198, v182
	v_add_f32_e32 v226, v228, v226
	v_add_f32_e32 v0, v229, v0
	s_waitcnt lgkmcnt(10)
	v_mfma_f32_32x32x16_bf16 v[34:49], v[102:105], v[134:137], v[34:49]
	ds_read_b64_tr_b16 v[126:127], v227 offset:60416
	ds_read_b64_tr_b16 v[128:129], v227 offset:60928
	v_add_f32_e32 v228, v167, v151
	v_add_f32_e32 v229, v199, v183
	v_add_f32_e32 v226, v228, v226
	v_add_f32_e32 v0, v229, v0
	s_waitcnt lgkmcnt(10)
	v_mfma_f32_32x32x16_bf16 v[34:49], v[106:109], v[138:141], v[34:49]
	ds_read_b64_tr_b16 v[130:131], v227 offset:61440
	ds_read_b64_tr_b16 v[132:133], v227 offset:61952
	v_add_f32_e32 v228, v168, v152
	v_add_f32_e32 v229, v200, v184
	v_add_f32_e32 v226, v228, v226
	v_add_f32_e32 v0, v229, v0
	s_waitcnt lgkmcnt(10)
	v_mfma_f32_32x32x16_bf16 v[34:49], v[110:113], v[142:145], v[34:49]
	ds_read_b64_tr_b16 v[134:135], v227 offset:62464
	ds_read_b64_tr_b16 v[136:137], v227 offset:62976
	v_add_f32_e32 v228, v169, v153
	v_add_f32_e32 v229, v201, v185
	v_add_f32_e32 v226, v228, v226
	v_add_f32_e32 v0, v229, v0
	s_waitcnt lgkmcnt(10)
	v_mfma_f32_32x32x16_bf16 v[18:33], v[98:101], v[114:117], v[18:33]
	ds_read_b64_tr_b16 v[138:139], v227 offset:63488
	ds_read_b64_tr_b16 v[140:141], v227 offset:64000
	v_add_f32_e32 v228, v170, v154
	v_add_f32_e32 v229, v202, v186
	v_add_f32_e32 v226, v228, v226
	v_add_f32_e32 v0, v229, v0
	s_waitcnt lgkmcnt(10)
	v_mfma_f32_32x32x16_bf16 v[18:33], v[102:105], v[118:121], v[18:33]
	ds_read_b64_tr_b16 v[142:143], v227 offset:64512
	ds_read_b64_tr_b16 v[144:145], v227 offset:65024
	v_add_f32_e32 v228, v171, v155
	v_add_f32_e32 v229, v203, v187
	v_add_f32_e32 v226, v228, v226
	v_add_f32_e32 v0, v229, v0
	s_waitcnt lgkmcnt(10)
	v_mfma_f32_32x32x16_bf16 v[18:33], v[106:109], v[122:125], v[18:33]
	v_add_f32_e32 v228, v172, v156
	v_add_f32_e32 v229, v204, v188
	v_add_f32_e32 v226, v228, v226
	v_add_f32_e32 v0, v229, v0
	s_waitcnt lgkmcnt(8)
	v_mfma_f32_32x32x16_bf16 v[18:33], v[110:113], v[126:129], v[18:33]
	v_add_f32_e32 v228, v173, v157
	v_add_f32_e32 v229, v205, v189
	v_add_f32_e32 v226, v228, v226
	v_add_f32_e32 v0, v229, v0
	s_waitcnt lgkmcnt(6)
	v_mfma_f32_32x32x16_bf16 v[2:17], v[98:101], v[130:133], v[2:17]
	v_add_f32_e32 v228, v174, v158
	v_add_f32_e32 v229, v206, v190
	v_add_f32_e32 v226, v228, v226
	v_add_f32_e32 v0, v229, v0
	s_waitcnt lgkmcnt(4)
	v_mfma_f32_32x32x16_bf16 v[2:17], v[102:105], v[134:137], v[2:17]
	v_add_f32_e32 v228, v175, v159
	v_add_f32_e32 v229, v207, v191
	v_add_f32_e32 v226, v228, v226
	v_add_f32_e32 v0, v229, v0
	s_waitcnt lgkmcnt(2)
	v_mfma_f32_32x32x16_bf16 v[2:17], v[106:109], v[138:141], v[2:17]
	v_add_f32_e32 v228, v176, v160
	v_add_f32_e32 v229, v208, v192
	v_add_f32_e32 v226, v228, v226
	v_add_f32_e32 v0, v229, v0
	s_waitcnt lgkmcnt(0)
	v_mfma_f32_32x32x16_bf16 v[2:17], v[110:113], v[142:145], v[2:17]
	v_add_f32_e32 v228, v177, v161
	v_add_f32_e32 v229, v209, v193
	v_add_f32_e32 v226, v228, v226
	v_add_f32_e32 v0, v229, v0
	v_add_f32_e32 v226, v226, v0
	v_add_f32_e32 v0, v237, v226
	s_addk_i32 s68, 0x80
	s_add_u32 s56, s56, 0x40000
	s_addc_u32 s57, s57, 0
	s_cmp_eq_u32 s74, s56
	s_cbranch_scc1 .LBB0_682
	v_mov_b32_e32 v235, v236
	s_mov_b32 s24, s75
	s_branch .LBB0_666

	.amdhsa_kernel _Z6mk_fwd6Params
		.amdhsa_group_segment_fixed_size 0
		.amdhsa_private_segment_fixed_size 0
		.amdhsa_kernarg_size 424
		.amdhsa_user_sgpr_count 2
		.amdhsa_user_sgpr_dispatch_ptr 0
		.amdhsa_user_sgpr_queue_ptr 0
		.amdhsa_user_sgpr_kernarg_segment_ptr 1
		.amdhsa_user_sgpr_dispatch_id 0
		.amdhsa_user_sgpr_kernarg_preload_length 0
		.amdhsa_user_sgpr_kernarg_preload_offset 0
		.amdhsa_user_sgpr_private_segment_size 0
		.amdhsa_uses_dynamic_stack 0
		.amdhsa_enable_private_segment 0
		.amdhsa_system_sgpr_workgroup_id_x 1
		.amdhsa_system_sgpr_workgroup_id_y 0
		.amdhsa_system_sgpr_workgroup_id_z 0
		.amdhsa_system_sgpr_workgroup_info 0
		.amdhsa_system_vgpr_workitem_id 2
		.amdhsa_next_free_vgpr 256
		.amdhsa_next_free_sgpr 102
		.amdhsa_accum_offset 256
		.amdhsa_reserve_vcc 1
		.amdhsa_float_round_mode_32 0
		.amdhsa_float_round_mode_16_64 0
		.amdhsa_float_denorm_mode_32 3
		.amdhsa_float_denorm_mode_16_64 3
		.amdhsa_dx10_clamp 1
		.amdhsa_ieee_mode 1
		.amdhsa_fp16_overflow 0
		.amdhsa_tg_split 0
		.amdhsa_exception_fp_ieee_invalid_op 0
		.amdhsa_exception_fp_denorm_src 0
		.amdhsa_exception_fp_ieee_div_zero 0
		.amdhsa_exception_fp_ieee_overflow 0
		.amdhsa_exception_fp_ieee_underflow 0
		.amdhsa_exception_fp_ieee_inexact 0
		.amdhsa_exception_int_div_zero 0
	.end_amdhsa_kernel

amdhsa.kernels:
  - .agpr_count:     0
    .args:
      - .offset:         0
        .size:           168
        .value_kind:     by_value
      - .offset:         168
        .size:           4
        .value_kind:     hidden_block_count_x
      - .offset:         172
        .size:           4
        .value_kind:     hidden_block_count_y
      - .offset:         176
        .size:           4
        .value_kind:     hidden_block_count_z
      - .offset:         180
        .size:           2
        .value_kind:     hidden_group_size_x
      - .offset:         182
        .size:           2
        .value_kind:     hidden_group_size_y
      - .offset:         184
        .size:           2
        .value_kind:     hidden_group_size_z
      - .offset:         186
        .size:           2
        .value_kind:     hidden_remainder_x
      - .offset:         188
        .size:           2
        .value_kind:     hidden_remainder_y
      - .offset:         190
        .size:           2
        .value_kind:     hidden_remainder_z
      - .offset:         208
        .size:           8
        .value_kind:     hidden_global_offset_x
      - .offset:         216
        .size:           8
        .value_kind:     hidden_global_offset_y
      - .offset:         224
        .size:           8
        .value_kind:     hidden_global_offset_z
      - .offset:         232
        .size:           2
        .value_kind:     hidden_grid_dims
      - .offset:         256
        .size:           8
        .value_kind:     hidden_multigrid_sync_arg
      - .offset:         288
        .size:           4
        .value_kind:     hidden_dynamic_lds_size
    .group_segment_fixed_size: 0
    .kernarg_segment_align: 8
    .kernarg_segment_size: 424
    .language:       OpenCL C
    .language_version:
      - 2
      - 0
    .max_flat_workgroup_size: 512
    .name:           _Z6mk_fwd6Params
    .private_segment_fixed_size: 0
    .sgpr_count:     108
    .sgpr_spill_count: 208
    .symbol:         _Z6mk_fwd6Params.kd
    .uniform_work_group_size: 1
    .uses_dynamic_stack: false
    .vgpr_count:     256
    .vgpr_spill_count: 0
    .wavefront_size: 64
